# RESID epilogue: xb loads hoisted to the top of the epilogue (13 in flight + 3 rolling), counted vmcnt instead of vmcnt(0) per row group
# speedup vs baseline: 1.0027x; 1.0018x over previous
; #define PG8_STAGE(bufoff, gbase, voff) do { _Pragma("unroll") for (int _i = 0; _i < 2; ++_i) \
;         __builtin_amdgcn_global_load_lds((const unsigned*)((const char*)(gbase) + (voff)[_i]), (PG8_LAS unsigned*)(lds + (bufoff) + ldsw + _i * 8192), 16, 0, 0); } while (0)
; #define PG8_LDA(dst, b, h) do { _Pragma("unroll") for (int m = 0; m < 4; ++m) _Pragma("unroll") for (int k = 0; k < 2; ++k) dst[m][k] = *(const PG8_LAS bf16x8*)(lds + PG8_SA(b, h) + aoff + m * 2048 + k * 1024); } while (0)
; #define PG8_LDB(dst, b, h) do { _Pragma("unroll") for (int n = 0; n < 2; ++n) _Pragma("unroll") for (int k = 0; k < 2; ++k) dst[n][k] = *(const PG8_LAS bf16x8*)(lds + PG8_SB(b, h) + boff + n * 2048 + k * 1024); } while (0)
; #define PG8_MMA(ai, bj, At, Bt) do { __builtin_amdgcn_s_setprio(1); _Pragma("unroll") for (int m = 0; m < 4; ++m) _Pragma("unroll") for (int n = 0; n < 2; ++n) _Pragma("unroll") for (int k = 0; k < 2; ++k) \
;         acc[ai][bj][m][n] = __builtin_amdgcn_mfma_f32_16x16x32_bf16(Bt[n][k], At[m][k], acc[ai][bj][m][n], 0, 0, 0); __builtin_amdgcn_s_setprio(0); } while (0)
; #define PG8_WAIT_V(n) asm volatile("s_waitcnt vmcnt(" #n ")" ::: "memory")
; #define PG8_BAR __builtin_amdgcn_s_barrier()
; template <class Epi, class Sched, bool ALIGN_EPI = false, bool SP2 = false>
; __device__ __forceinline__ void gemm_phase(PG8_LAS unsigned char* lds, const Gemm g, const Sched& S, const Epi& E, int wave_in) {
;     ...
;         for (int t = 0; t < nt; t += 2) {
;             const bool last = (t == nt - 2);
;             const char* a1 = cA + (size_t)(t + 1) * kstep;
;             const char* a2 = last ? nA : cA + (size_t)(t + 2) * kstep; const char* b2 = last ? nB : cB + (size_t)(t + 2) * kstep;
;             const char* a3 = a2 + kstep; const char* b3 = b2 + kstep;
;             if (last && has_next) S.a_ready(nxt);
;             if constexpr (SP2) {
;             PG8_LDB(B0, 0, 0); PG8_LDB(B1, 0, 1); PG8_SCHED; PG8_LDA(At, 0, 0); PG8_STAGE(PG8_SA(1, 1), a1 + hstepA, voffA);
;             PG8_WAIT_V(8); PG8_WAIT_L(0); PG8_BAR; PG8_MMA(0, 0, At, B0); PG8_MMA(0, 1, At, B1); PG8_BAR; PG8_SCHED;
;             PG8_LDA(At, 0, 1); PG8_STAGE(PG8_SB(0, 0), b2, voffB); PG8_STAGE(PG8_SB(0, 1), b2 + hstep, voffB); PG8_STAGE(PG8_SA(0, 0), a2, voffA);
;             PG8_WAIT_V(8); PG8_WAIT_L(0); PG8_BAR; PG8_MMA(1, 0, At, B0); PG8_MMA(1, 1, At, B1); PG8_BAR; PG8_SCHED;
.LBB0_404:
	s_add_i32 s43, s6, 2
	s_add_u32 s44, s4, 0x80
	s_addc_u32 s7, s5, 0
	s_add_i32 s46, 0, 0x10000
	s_cmp_eq_u32 s37, s6
	s_cselect_b32 s7, s21, s7
	s_cselect_b32 s6, s20, s44
	s_cselect_b32 s45, s23, s25
	s_cselect_b32 s44, s22, s24
	s_add_i32 s47, 0, 0x14000
	v_add_u32_e32 v168, s46, v149
	v_add_u32_e32 v184, s47, v149
	ds_read_b128 v[140:143], v168
	ds_read_b128 v[144:147], v168 offset:1024
	ds_read_b128 v[154:157], v168 offset:2048
	ds_read_b128 v[168:171], v168 offset:3072
	ds_read_b128 v[172:175], v184
	ds_read_b128 v[176:179], v184 offset:1024
	ds_read_b128 v[180:183], v184 offset:2048
	ds_read_b128 v[184:187], v184 offset:3072
	v_lshl_add_u64 v[192:193], s[4:5], 0, v[136:137]
	s_add_i32 m0, s28, 0xc000
	ds_read_b128 v[188:191], v153
	ds_read_b128 v[212:215], v153 offset:1024
	ds_read_b128 v[216:219], v153 offset:2048
	ds_read_b128 v[220:223], v153 offset:3072
	ds_read_b128 v[224:227], v153 offset:4096
	ds_read_b128 v[228:231], v153 offset:5120
	ds_read_b128 v[232:235], v153 offset:6144
	ds_read_b128 v[236:239], v153 offset:7168
	global_load_lds_dwordx4 v[192:193], off
	v_lshl_add_u64 v[192:193], s[4:5], 0, v[138:139]
	s_add_i32 m0, s28, 0xe000
	s_nop 0
	global_load_lds_dwordx4 v[192:193], off
	s_waitcnt vmcnt(8)
	s_waitcnt lgkmcnt(0)
	s_barrier
	s_setprio 1
	s_waitcnt lgkmcnt(0)
	v_mfma_f32_16x16x32_bf16 v[126:129], v[140:143], v[188:191], v[126:129]
	v_mfma_f32_16x16x32_bf16 v[122:125], v[154:157], v[188:191], v[122:125]
	v_mfma_f32_16x16x32_bf16 v[110:113], v[140:143], v[216:219], v[110:113]
	v_mfma_f32_16x16x32_bf16 v[106:109], v[154:157], v[216:219], v[106:109]
	v_mfma_f32_16x16x32_bf16 v[94:97], v[140:143], v[224:227], v[94:97]
	v_mfma_f32_16x16x32_bf16 v[90:93], v[154:157], v[224:227], v[90:93]
	v_mfma_f32_16x16x32_bf16 v[78:81], v[140:143], v[232:235], v[78:81]
	v_mfma_f32_16x16x32_bf16 v[74:77], v[154:157], v[232:235], v[74:77]
	v_mfma_f32_16x16x32_bf16 v[126:129], v[144:147], v[212:215], v[126:129]
	v_mfma_f32_16x16x32_bf16 v[122:125], v[168:171], v[212:215], v[122:125]
	v_mfma_f32_16x16x32_bf16 v[110:113], v[144:147], v[220:223], v[110:113]
	v_mfma_f32_16x16x32_bf16 v[106:109], v[168:171], v[220:223], v[106:109]
	v_mfma_f32_16x16x32_bf16 v[94:97], v[144:147], v[228:231], v[94:97]
	v_mfma_f32_16x16x32_bf16 v[90:93], v[168:171], v[228:231], v[90:93]
	v_mfma_f32_16x16x32_bf16 v[78:81], v[144:147], v[236:239], v[78:81]
	v_mfma_f32_16x16x32_bf16 v[74:77], v[168:171], v[236:239], v[74:77]
	s_setprio 0
	s_setprio 1
	v_mfma_f32_16x16x32_bf16 v[118:121], v[172:175], v[188:191], v[118:121]
	v_mfma_f32_16x16x32_bf16 v[114:117], v[180:183], v[188:191], v[114:117]
	v_mfma_f32_16x16x32_bf16 v[102:105], v[172:175], v[216:219], v[102:105]
	v_mfma_f32_16x16x32_bf16 v[98:101], v[180:183], v[216:219], v[98:101]
	v_mfma_f32_16x16x32_bf16 v[86:89], v[172:175], v[224:227], v[86:89]
	v_mfma_f32_16x16x32_bf16 v[82:85], v[180:183], v[224:227], v[82:85]
	v_mfma_f32_16x16x32_bf16 v[70:73], v[172:175], v[232:235], v[70:73]
	v_mfma_f32_16x16x32_bf16 v[66:69], v[180:183], v[232:235], v[66:69]
	v_mfma_f32_16x16x32_bf16 v[118:121], v[176:179], v[212:215], v[118:121]
	v_mfma_f32_16x16x32_bf16 v[114:117], v[184:187], v[212:215], v[114:117]
	v_mfma_f32_16x16x32_bf16 v[102:105], v[176:179], v[220:223], v[102:105]
	v_mfma_f32_16x16x32_bf16 v[98:101], v[184:187], v[220:223], v[98:101]
	v_mfma_f32_16x16x32_bf16 v[86:89], v[176:179], v[228:231], v[86:89]
	v_mfma_f32_16x16x32_bf16 v[82:85], v[184:187], v[228:231], v[82:85]
	v_mfma_f32_16x16x32_bf16 v[70:73], v[176:179], v[236:239], v[70:73]
	v_mfma_f32_16x16x32_bf16 v[66:69], v[184:187], v[236:239], v[66:69]
	s_setprio 0
	s_barrier
	s_add_i32 s46, s46, s27
	v_lshl_add_u64 v[192:193], s[44:45], 0, v[0:1]
	s_mov_b32 m0, s46
	ds_read_b128 v[188:191], v153 offset:16384
	ds_read_b128 v[212:215], v153 offset:17408
	ds_read_b128 v[216:219], v153 offset:18432
	ds_read_b128 v[220:223], v153 offset:19456
	ds_read_b128 v[224:227], v153 offset:20480
	ds_read_b128 v[228:231], v153 offset:21504
	ds_read_b128 v[232:235], v153 offset:22528
	ds_read_b128 v[236:239], v153 offset:23552
	global_load_lds_dwordx4 v[192:193], off
	s_add_i32 m0, s46, 0x2000
	v_lshl_add_u64 v[200:201], s[44:45], 0, v[130:131]
	s_add_u32 s44, s44, s78
	s_addc_u32 s45, s45, 0
	s_add_i32 s46, s47, s27
	global_load_lds_dwordx4 v[200:201], off
	v_lshl_add_u64 v[240:241], s[44:45], 0, v[0:1]
	s_mov_b32 m0, s46
	v_lshl_add_u64 v[242:243], s[44:45], 0, v[130:131]
	global_load_lds_dwordx4 v[240:241], off
	s_add_i32 m0, s46, 0x2000
	v_lshl_add_u64 v[244:245], s[6:7], 0, v[134:135]
	global_load_lds_dwordx4 v[242:243], off
	s_mov_b32 m0, s28
	v_lshl_add_u64 v[246:247], s[6:7], 0, v[132:133]
	global_load_lds_dwordx4 v[244:245], off
	s_mov_b32 m0, s29
	s_nop 0
	global_load_lds_dwordx4 v[246:247], off
	s_waitcnt vmcnt(8)
	s_waitcnt lgkmcnt(0)
	s_barrier
; #define PG8_STAGE(bufoff, gbase, voff) do { _Pragma("unroll") for (int _i = 0; _i < 2; ++_i) \
;         __builtin_amdgcn_global_load_lds((const unsigned*)((const char*)(gbase) + (voff)[_i]), (PG8_LAS unsigned*)(lds + (bufoff) + ldsw + _i * 8192), 16, 0, 0); } while (0)
; #define PG8_LDA(dst, b, h) do { _Pragma("unroll") for (int m = 0; m < 4; ++m) _Pragma("unroll") for (int k = 0; k < 2; ++k) dst[m][k] = *(const PG8_LAS bf16x8*)(lds + PG8_SA(b, h) + aoff + m * 2048 + k * 1024); } while (0)
; #define PG8_LDB(dst, b, h) do { _Pragma("unroll") for (int n = 0; n < 2; ++n) _Pragma("unroll") for (int k = 0; k < 2; ++k) dst[n][k] = *(const PG8_LAS bf16x8*)(lds + PG8_SB(b, h) + boff + n * 2048 + k * 1024); } while (0)
; #define PG8_MMA(ai, bj, At, Bt) do { __builtin_amdgcn_s_setprio(1); _Pragma("unroll") for (int m = 0; m < 4; ++m) _Pragma("unroll") for (int n = 0; n < 2; ++n) _Pragma("unroll") for (int k = 0; k < 2; ++k) \
;         acc[ai][bj][m][n] = __builtin_amdgcn_mfma_f32_16x16x32_bf16(Bt[n][k], At[m][k], acc[ai][bj][m][n], 0, 0, 0); __builtin_amdgcn_s_setprio(0); } while (0)
; #define PG8_WAIT_V(n) asm volatile("s_waitcnt vmcnt(" #n ")" ::: "memory")
; #define PG8_WAIT_L(n) asm volatile("s_waitcnt lgkmcnt(" #n ")" ::: "memory")
; #define PG8_BAR __builtin_amdgcn_s_barrier()
; #define PG8_SCHED __builtin_amdgcn_sched_barrier(0)
; template <class Epi, class Sched, bool ALIGN_EPI = false, bool SP2 = false>
; __device__ __forceinline__ void gemm_phase(PG8_LAS unsigned char* lds, const Gemm g, const Sched& S, const Epi& E, int wave_in) {
;     ...
;             PG8_WAIT_V(8); PG8_WAIT_L(0); PG8_BAR; PG8_MMA(1, 0, At, B0); PG8_MMA(1, 1, At, B1); PG8_BAR; PG8_SCHED;
;             PG8_LDB(B0, 1, 0); PG8_LDB(B1, 1, 1); PG8_SCHED; PG8_LDA(At, 1, 0); PG8_STAGE(PG8_SA(0, 1), a2 + hstepA, voffA);
;             PG8_WAIT_V(8); PG8_WAIT_L(0); PG8_BAR; PG8_MMA(0, 0, At, B0); PG8_MMA(0, 1, At, B1); PG8_BAR; PG8_SCHED;
	s_setprio 1
	s_waitcnt lgkmcnt(0)
	v_mfma_f32_16x16x32_bf16 v[62:65], v[140:143], v[188:191], v[62:65]
	v_mfma_f32_16x16x32_bf16 v[58:61], v[154:157], v[188:191], v[58:61]
	v_mfma_f32_16x16x32_bf16 v[46:49], v[140:143], v[216:219], v[46:49]
	v_mfma_f32_16x16x32_bf16 v[42:45], v[154:157], v[216:219], v[42:45]
	v_mfma_f32_16x16x32_bf16 v[30:33], v[140:143], v[224:227], v[30:33]
	v_mfma_f32_16x16x32_bf16 v[26:29], v[154:157], v[224:227], v[26:29]
	v_mfma_f32_16x16x32_bf16 v[14:17], v[140:143], v[232:235], v[14:17]
	v_mfma_f32_16x16x32_bf16 v[10:13], v[154:157], v[232:235], v[10:13]
	v_mfma_f32_16x16x32_bf16 v[62:65], v[144:147], v[212:215], v[62:65]
	v_mfma_f32_16x16x32_bf16 v[58:61], v[168:171], v[212:215], v[58:61]
	v_mfma_f32_16x16x32_bf16 v[46:49], v[144:147], v[220:223], v[46:49]
	v_mfma_f32_16x16x32_bf16 v[42:45], v[168:171], v[220:223], v[42:45]
	v_mfma_f32_16x16x32_bf16 v[30:33], v[144:147], v[228:231], v[30:33]
	v_mfma_f32_16x16x32_bf16 v[26:29], v[168:171], v[228:231], v[26:29]
	v_mfma_f32_16x16x32_bf16 v[14:17], v[144:147], v[236:239], v[14:17]
	v_mfma_f32_16x16x32_bf16 v[10:13], v[168:171], v[236:239], v[10:13]
	s_setprio 0
	s_setprio 1
	v_mfma_f32_16x16x32_bf16 v[54:57], v[172:175], v[188:191], v[54:57]
	v_mfma_f32_16x16x32_bf16 v[50:53], v[180:183], v[188:191], v[50:53]
	v_mfma_f32_16x16x32_bf16 v[38:41], v[172:175], v[216:219], v[38:41]
	v_mfma_f32_16x16x32_bf16 v[34:37], v[180:183], v[216:219], v[34:37]
	v_mfma_f32_16x16x32_bf16 v[22:25], v[172:175], v[224:227], v[22:25]
	v_mfma_f32_16x16x32_bf16 v[18:21], v[180:183], v[224:227], v[18:21]
	v_mfma_f32_16x16x32_bf16 v[6:9], v[172:175], v[232:235], v[6:9]
	v_mfma_f32_16x16x32_bf16 v[2:5], v[180:183], v[232:235], v[2:5]
	v_mfma_f32_16x16x32_bf16 v[54:57], v[176:179], v[212:215], v[54:57]
	v_mfma_f32_16x16x32_bf16 v[50:53], v[184:187], v[212:215], v[50:53]
	v_mfma_f32_16x16x32_bf16 v[38:41], v[176:179], v[220:223], v[38:41]
	v_mfma_f32_16x16x32_bf16 v[34:37], v[184:187], v[220:223], v[34:37]
	v_mfma_f32_16x16x32_bf16 v[22:25], v[176:179], v[228:231], v[22:25]
	v_mfma_f32_16x16x32_bf16 v[18:21], v[184:187], v[228:231], v[18:21]
	v_mfma_f32_16x16x32_bf16 v[6:9], v[176:179], v[236:239], v[6:9]
	v_mfma_f32_16x16x32_bf16 v[2:5], v[184:187], v[236:239], v[2:5]
	s_setprio 0
	s_barrier
	s_add_i32 s44, 0, 0x18000
	s_add_i32 s45, 0, 0x1c000
	v_add_u32_e32 v168, s44, v149
	v_add_u32_e32 v184, s45, v149
	ds_read_b128 v[140:143], v168
	ds_read_b128 v[144:147], v168 offset:1024
	ds_read_b128 v[154:157], v168 offset:2048
	ds_read_b128 v[168:171], v168 offset:3072
	ds_read_b128 v[172:175], v184
	ds_read_b128 v[176:179], v184 offset:1024
	ds_read_b128 v[180:183], v184 offset:2048
	ds_read_b128 v[184:187], v184 offset:3072
	s_add_u32 s6, s6, s78
	s_addc_u32 s7, s7, 0
	s_mov_b32 m0, s30
	v_lshl_add_u64 v[248:249], s[6:7], 0, v[134:135]
	ds_read_b128 v[188:191], v153 offset:32768
	ds_read_b128 v[212:215], v153 offset:33792
	ds_read_b128 v[216:219], v153 offset:34816
	ds_read_b128 v[220:223], v153 offset:35840
	ds_read_b128 v[224:227], v153 offset:36864
	ds_read_b128 v[228:231], v153 offset:37888
	ds_read_b128 v[232:235], v153 offset:38912
	ds_read_b128 v[236:239], v153 offset:39936
	global_load_lds_dwordx4 v[248:249], off
	v_lshl_add_u64 v[248:249], s[6:7], 0, v[132:133]
	s_mov_b32 m0, s31
	s_nop 0
	global_load_lds_dwordx4 v[248:249], off
	s_waitcnt vmcnt(8)
	s_waitcnt lgkmcnt(0)
	s_barrier
	s_setprio 1
	s_waitcnt lgkmcnt(0)
	v_mfma_f32_16x16x32_bf16 v[126:129], v[140:143], v[188:191], v[126:129]
	v_mfma_f32_16x16x32_bf16 v[122:125], v[154:157], v[188:191], v[122:125]
	v_mfma_f32_16x16x32_bf16 v[110:113], v[140:143], v[216:219], v[110:113]
	v_mfma_f32_16x16x32_bf16 v[106:109], v[154:157], v[216:219], v[106:109]
	v_mfma_f32_16x16x32_bf16 v[94:97], v[140:143], v[224:227], v[94:97]
	v_mfma_f32_16x16x32_bf16 v[90:93], v[154:157], v[224:227], v[90:93]
	v_mfma_f32_16x16x32_bf16 v[78:81], v[140:143], v[232:235], v[78:81]
	v_mfma_f32_16x16x32_bf16 v[74:77], v[154:157], v[232:235], v[74:77]
	v_mfma_f32_16x16x32_bf16 v[126:129], v[144:147], v[212:215], v[126:129]
	v_mfma_f32_16x16x32_bf16 v[122:125], v[168:171], v[212:215], v[122:125]
	v_mfma_f32_16x16x32_bf16 v[110:113], v[144:147], v[220:223], v[110:113]
	v_mfma_f32_16x16x32_bf16 v[106:109], v[168:171], v[220:223], v[106:109]
	v_mfma_f32_16x16x32_bf16 v[94:97], v[144:147], v[228:231], v[94:97]
	v_mfma_f32_16x16x32_bf16 v[90:93], v[168:171], v[228:231], v[90:93]
	v_mfma_f32_16x16x32_bf16 v[78:81], v[144:147], v[236:239], v[78:81]
	v_mfma_f32_16x16x32_bf16 v[74:77], v[168:171], v[236:239], v[74:77]
	s_setprio 0
	s_setprio 1
	v_mfma_f32_16x16x32_bf16 v[118:121], v[172:175], v[188:191], v[118:121]
	v_mfma_f32_16x16x32_bf16 v[114:117], v[180:183], v[188:191], v[114:117]
	v_mfma_f32_16x16x32_bf16 v[102:105], v[172:175], v[216:219], v[102:105]
	v_mfma_f32_16x16x32_bf16 v[98:101], v[180:183], v[216:219], v[98:101]
	v_mfma_f32_16x16x32_bf16 v[86:89], v[172:175], v[224:227], v[86:89]
	v_mfma_f32_16x16x32_bf16 v[82:85], v[180:183], v[224:227], v[82:85]
	v_mfma_f32_16x16x32_bf16 v[70:73], v[172:175], v[232:235], v[70:73]
	v_mfma_f32_16x16x32_bf16 v[66:69], v[180:183], v[232:235], v[66:69]
	v_mfma_f32_16x16x32_bf16 v[118:121], v[176:179], v[212:215], v[118:121]
	v_mfma_f32_16x16x32_bf16 v[114:117], v[184:187], v[212:215], v[114:117]
	v_mfma_f32_16x16x32_bf16 v[102:105], v[176:179], v[220:223], v[102:105]
	v_mfma_f32_16x16x32_bf16 v[98:101], v[184:187], v[220:223], v[98:101]
	v_mfma_f32_16x16x32_bf16 v[86:89], v[176:179], v[228:231], v[86:89]
	v_mfma_f32_16x16x32_bf16 v[82:85], v[184:187], v[228:231], v[82:85]
	v_mfma_f32_16x16x32_bf16 v[70:73], v[176:179], v[236:239], v[70:73]
	v_mfma_f32_16x16x32_bf16 v[66:69], v[184:187], v[236:239], v[66:69]
	s_setprio 0
	s_barrier
; __device__ __forceinline__ void unpack8(u32x4 w, f32x4& a, f32x4& b) { a = (f32x4){bf_lo(w.x), bf_hi(w.x), bf_lo(w.y), bf_hi(w.y)}; b = (f32x4){bf_lo(w.z), bf_hi(w.z), bf_lo(w.w), bf_hi(w.w)}; }
; #define PG8_STAGE(bufoff, gbase, voff) do { _Pragma("unroll") for (int _i = 0; _i < 2; ++_i) \
;         __builtin_amdgcn_global_load_lds((const unsigned*)((const char*)(gbase) + (voff)[_i]), (PG8_LAS unsigned*)(lds + (bufoff) + ldsw + _i * 8192), 16, 0, 0); } while (0)
; #define PG8_LDA(dst, b, h) do { _Pragma("unroll") for (int m = 0; m < 4; ++m) _Pragma("unroll") for (int k = 0; k < 2; ++k) dst[m][k] = *(const PG8_LAS bf16x8*)(lds + PG8_SA(b, h) + aoff + m * 2048 + k * 1024); } while (0)
; #define PG8_MMA(ai, bj, At, Bt) do { __builtin_amdgcn_s_setprio(1); _Pragma("unroll") for (int m = 0; m < 4; ++m) _Pragma("unroll") for (int n = 0; n < 2; ++n) _Pragma("unroll") for (int k = 0; k < 2; ++k) \
;         acc[ai][bj][m][n] = __builtin_amdgcn_mfma_f32_16x16x32_bf16(Bt[n][k], At[m][k], acc[ai][bj][m][n], 0, 0, 0); __builtin_amdgcn_s_setprio(0); } while (0)
; #define PG8_WAIT_V(n) asm volatile("s_waitcnt vmcnt(" #n ")" ::: "memory")
; #define PG8_WAIT_L(n) asm volatile("s_waitcnt lgkmcnt(" #n ")" ::: "memory")
; #define PG8_BAR __builtin_amdgcn_s_barrier()
; #define PG8_SCHED __builtin_amdgcn_sched_barrier(0)
;     __device__ __forceinline__ void operator()(const f32x4 (&acc)[2][2][4][2], const Unit& u, int wr, int wc, int fr, int fq) const {
;     ...
;                     } else if (MODE == EP_RESID) {
;                         f32x4 x0, x1; unpack8(*(const u32x4*)(xb + row * ldc + col), x0, x1); x0 = x0 + v0; x1 = x1 + v1;
;                         if (O) { *(f32x4*)((float*)O + row * ldc + col) = x0; *(f32x4*)((float*)O + row * ldc + col + 4) = x1; }
; template <class Epi, class Sched, bool ALIGN_EPI = false, bool SP2 = false>
; __device__ __forceinline__ void gemm_phase(PG8_LAS unsigned char* lds, const Gemm g, const Sched& S, const Epi& E, int wave_in) {
;     ...
;             PG8_LDA(At, 1, 1); PG8_STAGE(PG8_SB(1, 0), b3, voffB); PG8_STAGE(PG8_SB(1, 1), b3 + hstep, voffB); PG8_STAGE(PG8_SA(1, 0), a3, voffA);
;             PG8_WAIT_V(8); PG8_WAIT_L(0); PG8_BAR; PG8_MMA(1, 0, At, B0); PG8_MMA(1, 1, At, B1); PG8_BAR; PG8_SCHED;
	s_add_i32 s6, s44, s27
	v_lshl_add_u64 v[192:193], v[192:193], 0, s[84:85]
	s_mov_b32 m0, s6
	ds_read_b128 v[188:191], v153 offset:49152
	ds_read_b128 v[212:215], v153 offset:50176
	ds_read_b128 v[216:219], v153 offset:51200
	ds_read_b128 v[220:223], v153 offset:52224
	ds_read_b128 v[224:227], v153 offset:53248
	ds_read_b128 v[228:231], v153 offset:54272
	ds_read_b128 v[232:235], v153 offset:55296
	ds_read_b128 v[236:239], v153 offset:56320
	global_load_lds_dwordx4 v[192:193], off
	v_lshl_add_u64 v[192:193], v[200:201], 0, s[84:85]
	s_add_i32 m0, s6, 0x2000
	s_add_i32 s6, s45, s27
	global_load_lds_dwordx4 v[192:193], off
	v_lshl_add_u64 v[192:193], v[240:241], 0, s[84:85]
	s_mov_b32 m0, s6
	s_nop 0
	global_load_lds_dwordx4 v[192:193], off
	v_lshl_add_u64 v[192:193], v[242:243], 0, s[84:85]
	s_add_i32 m0, s6, 0x2000
	s_nop 0
	global_load_lds_dwordx4 v[192:193], off
	v_lshl_add_u64 v[192:193], v[244:245], 0, s[84:85]
	s_mov_b32 m0, s34
	s_nop 0
	global_load_lds_dwordx4 v[192:193], off
	v_lshl_add_u64 v[192:193], v[246:247], 0, s[84:85]
	s_mov_b32 m0, s35
	s_nop 0
	global_load_lds_dwordx4 v[192:193], off
	s_waitcnt vmcnt(8)
	s_waitcnt lgkmcnt(0)
	s_barrier
	s_setprio 1
	s_waitcnt lgkmcnt(0)
	v_mfma_f32_16x16x32_bf16 v[62:65], v[140:143], v[188:191], v[62:65]
	v_mfma_f32_16x16x32_bf16 v[58:61], v[154:157], v[188:191], v[58:61]
	v_mfma_f32_16x16x32_bf16 v[46:49], v[140:143], v[216:219], v[46:49]
	v_mfma_f32_16x16x32_bf16 v[42:45], v[154:157], v[216:219], v[42:45]
	v_mfma_f32_16x16x32_bf16 v[30:33], v[140:143], v[224:227], v[30:33]
	v_mfma_f32_16x16x32_bf16 v[26:29], v[154:157], v[224:227], v[26:29]
	v_mfma_f32_16x16x32_bf16 v[14:17], v[140:143], v[232:235], v[14:17]
	v_mfma_f32_16x16x32_bf16 v[10:13], v[154:157], v[232:235], v[10:13]
	v_mfma_f32_16x16x32_bf16 v[62:65], v[144:147], v[212:215], v[62:65]
	v_mfma_f32_16x16x32_bf16 v[58:61], v[168:171], v[212:215], v[58:61]
	v_mfma_f32_16x16x32_bf16 v[46:49], v[144:147], v[220:223], v[46:49]
	v_mfma_f32_16x16x32_bf16 v[42:45], v[168:171], v[220:223], v[42:45]
	v_mfma_f32_16x16x32_bf16 v[30:33], v[144:147], v[228:231], v[30:33]
	v_mfma_f32_16x16x32_bf16 v[26:29], v[168:171], v[228:231], v[26:29]
	v_mfma_f32_16x16x32_bf16 v[14:17], v[144:147], v[236:239], v[14:17]
	v_mfma_f32_16x16x32_bf16 v[10:13], v[168:171], v[236:239], v[10:13]
	s_setprio 0
	s_setprio 1
	v_mfma_f32_16x16x32_bf16 v[54:57], v[172:175], v[188:191], v[54:57]
	v_mfma_f32_16x16x32_bf16 v[50:53], v[180:183], v[188:191], v[50:53]
	v_mfma_f32_16x16x32_bf16 v[38:41], v[172:175], v[216:219], v[38:41]
	v_mfma_f32_16x16x32_bf16 v[34:37], v[180:183], v[216:219], v[34:37]
	v_mfma_f32_16x16x32_bf16 v[22:25], v[172:175], v[224:227], v[22:25]
	v_mfma_f32_16x16x32_bf16 v[18:21], v[180:183], v[224:227], v[18:21]
	v_mfma_f32_16x16x32_bf16 v[6:9], v[172:175], v[232:235], v[6:9]
	v_mfma_f32_16x16x32_bf16 v[2:5], v[180:183], v[232:235], v[2:5]
	v_mfma_f32_16x16x32_bf16 v[54:57], v[176:179], v[212:215], v[54:57]
	v_mfma_f32_16x16x32_bf16 v[50:53], v[184:187], v[212:215], v[50:53]
	v_mfma_f32_16x16x32_bf16 v[38:41], v[176:179], v[220:223], v[38:41]
	v_mfma_f32_16x16x32_bf16 v[34:37], v[184:187], v[220:223], v[34:37]
	v_mfma_f32_16x16x32_bf16 v[22:25], v[176:179], v[228:231], v[22:25]
	v_mfma_f32_16x16x32_bf16 v[18:21], v[184:187], v[228:231], v[18:21]
	v_mfma_f32_16x16x32_bf16 v[6:9], v[176:179], v[236:239], v[6:9]
	v_mfma_f32_16x16x32_bf16 v[2:5], v[184:187], v[236:239], v[2:5]
	s_setprio 0
	s_barrier
	s_add_u32 s4, s4, 0x100
	s_addc_u32 s5, s5, 0
	s_add_u32 s24, s24, 0x100
	s_addc_u32 s25, s25, 0
	s_cmp_ge_u32 s43, s36
	s_mov_b32 s6, s43
	s_cbranch_scc0 .LBB0_404
	v_readlane_b32 s98, v253, 60
	v_readlane_b32 s99, v253, 61
	v_lshl_add_u32 v166, s42, 8, v148
	v_lshl_or_b32 v167, s41, 8, v152
	v_lshlrev_b32_e32 v167, 1, v167
	s_nop 1
	v_add_u32_e32 v199, 0, v166
	v_lshl_add_u32 v205, v199, 12, v167
	global_load_dwordx4 v[172:175], v205, s[98:99]
	global_load_dwordx4 v[176:179], v205, s[98:99] offset:256
	v_add_u32_e32 v199, 16, v166
	v_lshl_add_u32 v205, v199, 12, v167
	global_load_dwordx4 v[180:183], v205, s[98:99]
	global_load_dwordx4 v[184:187], v205, s[98:99] offset:256
	v_add_u32_e32 v199, 32, v166
	v_lshl_add_u32 v205, v199, 12, v167
	global_load_dwordx4 v[188:191], v205, s[98:99]
	global_load_dwordx4 v[212:215], v205, s[98:99] offset:256
	v_add_u32_e32 v199, 48, v166
	v_lshl_add_u32 v205, v199, 12, v167
	global_load_dwordx4 v[216:219], v205, s[98:99]
	global_load_dwordx4 v[220:223], v205, s[98:99] offset:256
	v_add_u32_e32 v199, 128, v166
	v_lshl_add_u32 v205, v199, 12, v167
	global_load_dwordx4 v[224:227], v205, s[98:99]
	global_load_dwordx4 v[228:231], v205, s[98:99] offset:256
	v_add_u32_e32 v199, 144, v166
	v_lshl_add_u32 v205, v199, 12, v167
	global_load_dwordx4 v[232:235], v205, s[98:99]
	global_load_dwordx4 v[236:239], v205, s[98:99] offset:256
	v_add_u32_e32 v199, 160, v166
	v_lshl_add_u32 v205, v199, 12, v167
	global_load_dwordx4 v[206:209], v205, s[98:99]
	s_and_b64 vcc, exec, s[16:17]
	s_cbranch_vccz .LBB0_407
	s_barrier
.LBB0_407:
	v_lshl_add_u32 v140, s42, 8, v148
	v_ashrrev_i32_e32 v141, 31, v140
	v_readlane_b32 s4, v253, 60
	v_lshl_or_b32 v142, s41, 8, v152
	v_lshlrev_b64 v[144:145], 12, v[140:141]
	v_readlane_b32 s5, v253, 61
	v_ashrrev_i32_e32 v143, 31, v142
	v_cndmask_b32_e64 v146, 0, 1, s[18:19]
	v_lshl_add_u64 v[144:145], s[4:5], 0, v[144:145]
	v_lshl_add_u64 v[144:145], v[142:143], 1, v[144:145]
	s_nop 0
	v_cmp_ne_u32_e64 s[4:5], 1, v146
	v_lshlrev_b64 v[146:147], 11, v[140:141]
	s_andn2_b64 vcc, exec, s[18:19]
	v_lshl_add_u64 v[146:147], v[146:147], 2, s[2:3]
	s_nop 0
	s_waitcnt vmcnt(12)
	v_lshlrev_b32_e32 v168, 16, v172
	v_and_b32_e32 v169, 0xffff0000, v172
	v_lshlrev_b32_e32 v154, 16, v173
	v_and_b32_e32 v155, 0xffff0000, v173
	v_lshlrev_b32_e32 v170, 16, v174
	v_and_b32_e32 v171, 0xffff0000, v174
	v_lshlrev_b32_e32 v156, 16, v175
	v_and_b32_e32 v157, 0xffff0000, v175
	v_add_u32_e32 v199, 160, v166
	v_lshl_add_u32 v205, v199, 12, v167
	global_load_dwordx4 v[172:175], v205, s[98:99] offset:256
	v_pk_add_f32 v[128:129], v[128:129], v[154:155]
	v_pk_add_f32 v[126:127], v[126:127], v[168:169]
	v_pk_add_f32 v[124:125], v[124:125], v[156:157]
	v_pk_add_f32 v[122:123], v[122:123], v[170:171]
	s_cbranch_vccnz .LBB0_409
	v_lshl_add_u64 v[154:155], v[142:143], 2, v[146:147]
	global_store_dwordx4 v[154:155], v[126:129], off
	global_store_dwordx4 v[154:155], v[122:125], off offset:16

; __device__ __forceinline__ void unpack8(u32x4 w, f32x4& a, f32x4& b) { a = (f32x4){bf_lo(w.x), bf_hi(w.x), bf_lo(w.y), bf_hi(w.y)}; b = (f32x4){bf_lo(w.z), bf_hi(w.z), bf_lo(w.w), bf_hi(w.w)}; }
;     __device__ __forceinline__ void operator()(const f32x4 (&acc)[2][2][4][2], const Unit& u, int wr, int wc, int fr, int fq) const {
;     ...
;                     } else if (MODE == EP_RESID) {
;                         f32x4 x0, x1; unpack8(*(const u32x4*)(xb + row * ldc + col), x0, x1); x0 = x0 + v0; x1 = x1 + v1;
;                         if (O) { *(f32x4*)((float*)O + row * ldc + col) = x0; *(f32x4*)((float*)O + row * ldc + col + 4) = x1; }
.LBB0_411:
	s_nop 0
	s_and_b64 vcc, exec, s[4:5]
	s_nop 0
	s_waitcnt vmcnt(12)
	v_lshlrev_b32_e32 v126, 16, v176
	v_and_b32_e32 v127, 0xffff0000, v176
	v_lshlrev_b32_e32 v122, 16, v177
	v_and_b32_e32 v123, 0xffff0000, v177
	v_lshlrev_b32_e32 v128, 16, v178
	v_and_b32_e32 v129, 0xffff0000, v178
	v_lshlrev_b32_e32 v124, 16, v179
	v_and_b32_e32 v125, 0xffff0000, v179
	v_add_u32_e32 v199, 176, v166
	v_lshl_add_u32 v205, v199, 12, v167
	global_load_dwordx4 v[176:179], v205, s[98:99]
	v_pk_add_f32 v[120:121], v[120:121], v[122:123]
	v_pk_add_f32 v[118:119], v[118:119], v[126:127]
	v_pk_add_f32 v[116:117], v[116:117], v[124:125]
	v_pk_add_f32 v[114:115], v[114:115], v[128:129]
	s_cbranch_vccnz .LBB0_413
	v_lshl_add_u64 v[122:123], v[142:143], 2, v[146:147]
	global_store_dwordx4 v[122:123], v[118:121], off offset:512
	global_store_dwordx4 v[122:123], v[114:117], off offset:528

; __device__ __forceinline__ void unpack8(u32x4 w, f32x4& a, f32x4& b) { a = (f32x4){bf_lo(w.x), bf_hi(w.x), bf_lo(w.y), bf_hi(w.y)}; b = (f32x4){bf_lo(w.z), bf_hi(w.z), bf_lo(w.w), bf_hi(w.w)}; }
;     __device__ __forceinline__ void operator()(const f32x4 (&acc)[2][2][4][2], const Unit& u, int wr, int wc, int fr, int fq) const {
;     ...
;                     } else if (MODE == EP_RESID) {
;                         f32x4 x0, x1; unpack8(*(const u32x4*)(xb + row * ldc + col), x0, x1); x0 = x0 + v0; x1 = x1 + v1;
;                         if (O) { *(f32x4*)((float*)O + row * ldc + col) = x0; *(f32x4*)((float*)O + row * ldc + col + 4) = x1; }
.LBB0_417:
	v_or_b32_e32 v120, 16, v140
	v_ashrrev_i32_e32 v121, 31, v120
	v_readlane_b32 s24, v253, 60
	v_lshlrev_b64 v[114:115], 12, v[120:121]
	v_readlane_b32 s25, v253, 61
	v_lshlrev_b64 v[120:121], 11, v[120:121]
	s_and_b64 vcc, exec, s[4:5]
	v_lshl_add_u64 v[114:115], s[24:25], 0, v[114:115]
	v_lshl_add_u64 v[114:115], v[142:143], 1, v[114:115]
	s_waitcnt lgkmcnt(0)
	s_nop 0
	s_nop 0
	s_waitcnt vmcnt(12)
	v_lshlrev_b32_e32 v122, 16, v180
	v_and_b32_e32 v123, 0xffff0000, v180
	v_lshlrev_b32_e32 v116, 16, v181
	v_and_b32_e32 v117, 0xffff0000, v181
	v_lshlrev_b32_e32 v124, 16, v182
	v_and_b32_e32 v125, 0xffff0000, v182
	v_lshlrev_b32_e32 v118, 16, v183
	v_and_b32_e32 v119, 0xffff0000, v183
	v_add_u32_e32 v199, 176, v166
	v_lshl_add_u32 v205, v199, 12, v167
	global_load_dwordx4 v[180:183], v205, s[98:99] offset:256
	v_pk_add_f32 v[112:113], v[112:113], v[116:117]
	v_pk_add_f32 v[110:111], v[110:111], v[122:123]
	v_pk_add_f32 v[108:109], v[108:109], v[118:119]
	v_pk_add_f32 v[106:107], v[106:107], v[124:125]
	v_lshl_add_u64 v[116:117], v[120:121], 2, s[2:3]
	s_cbranch_vccnz .LBB0_419
	v_lshl_add_u64 v[118:119], v[142:143], 2, v[116:117]
	global_store_dwordx4 v[118:119], v[110:113], off
	global_store_dwordx4 v[118:119], v[106:109], off offset:16

; __device__ __forceinline__ void unpack8(u32x4 w, f32x4& a, f32x4& b) { a = (f32x4){bf_lo(w.x), bf_hi(w.x), bf_lo(w.y), bf_hi(w.y)}; b = (f32x4){bf_lo(w.z), bf_hi(w.z), bf_lo(w.w), bf_hi(w.w)}; }
;     __device__ __forceinline__ void operator()(const f32x4 (&acc)[2][2][4][2], const Unit& u, int wr, int wc, int fr, int fq) const {
;     ...
;                     } else if (MODE == EP_RESID) {
;                         f32x4 x0, x1; unpack8(*(const u32x4*)(xb + row * ldc + col), x0, x1); x0 = x0 + v0; x1 = x1 + v1;
;                         if (O) { *(f32x4*)((float*)O + row * ldc + col) = x0; *(f32x4*)((float*)O + row * ldc + col + 4) = x1; }
.LBB0_421:
	s_nop 0
	s_and_b64 vcc, exec, s[4:5]
	s_nop 0
	s_waitcnt vmcnt(12)
	v_lshlrev_b32_e32 v110, 16, v184
	v_and_b32_e32 v111, 0xffff0000, v184
	v_lshlrev_b32_e32 v106, 16, v185
	v_and_b32_e32 v107, 0xffff0000, v185
	v_lshlrev_b32_e32 v112, 16, v186
	v_and_b32_e32 v113, 0xffff0000, v186
	v_lshlrev_b32_e32 v108, 16, v187
	v_and_b32_e32 v109, 0xffff0000, v187
	v_pk_add_f32 v[104:105], v[104:105], v[106:107]
	v_pk_add_f32 v[102:103], v[102:103], v[110:111]
	v_pk_add_f32 v[100:101], v[100:101], v[108:109]
	v_pk_add_f32 v[98:99], v[98:99], v[112:113]
	s_cbranch_vccnz .LBB0_423
	v_lshl_add_u64 v[106:107], v[142:143], 2, v[116:117]
	global_store_dwordx4 v[106:107], v[102:105], off offset:512
	global_store_dwordx4 v[106:107], v[98:101], off offset:528

; __device__ __forceinline__ void unpack8(u32x4 w, f32x4& a, f32x4& b) { a = (f32x4){bf_lo(w.x), bf_hi(w.x), bf_lo(w.y), bf_hi(w.y)}; b = (f32x4){bf_lo(w.z), bf_hi(w.z), bf_lo(w.w), bf_hi(w.w)}; }
;     __device__ __forceinline__ void operator()(const f32x4 (&acc)[2][2][4][2], const Unit& u, int wr, int wc, int fr, int fq) const {
;     ...
;                     } else if (MODE == EP_RESID) {
;                         f32x4 x0, x1; unpack8(*(const u32x4*)(xb + row * ldc + col), x0, x1); x0 = x0 + v0; x1 = x1 + v1;
;                         if (O) { *(f32x4*)((float*)O + row * ldc + col) = x0; *(f32x4*)((float*)O + row * ldc + col + 4) = x1; }
.LBB0_427:
	v_or_b32_e32 v104, 32, v140
	v_ashrrev_i32_e32 v105, 31, v104
	v_readlane_b32 s24, v253, 60
	v_lshlrev_b64 v[98:99], 12, v[104:105]
	v_readlane_b32 s25, v253, 61
	v_lshlrev_b64 v[104:105], 11, v[104:105]
	s_and_b64 vcc, exec, s[4:5]
	v_lshl_add_u64 v[98:99], s[24:25], 0, v[98:99]
	v_lshl_add_u64 v[98:99], v[142:143], 1, v[98:99]
	s_waitcnt lgkmcnt(0)
	s_nop 0
	s_nop 0
	s_waitcnt vmcnt(11)
	v_lshlrev_b32_e32 v106, 16, v188
	v_and_b32_e32 v107, 0xffff0000, v188
	v_lshlrev_b32_e32 v100, 16, v189
	v_and_b32_e32 v101, 0xffff0000, v189
	v_lshlrev_b32_e32 v108, 16, v190
	v_and_b32_e32 v109, 0xffff0000, v190
	v_lshlrev_b32_e32 v102, 16, v191
	v_and_b32_e32 v103, 0xffff0000, v191
	v_pk_add_f32 v[96:97], v[96:97], v[100:101]
	v_pk_add_f32 v[94:95], v[94:95], v[106:107]
	v_pk_add_f32 v[92:93], v[92:93], v[102:103]
	v_pk_add_f32 v[90:91], v[90:91], v[108:109]
	v_lshl_add_u64 v[100:101], v[104:105], 2, s[2:3]
	s_cbranch_vccnz .LBB0_429
	v_lshl_add_u64 v[102:103], v[142:143], 2, v[100:101]
	global_store_dwordx4 v[102:103], v[94:97], off
	global_store_dwordx4 v[102:103], v[90:93], off offset:16

; __device__ __forceinline__ void unpack8(u32x4 w, f32x4& a, f32x4& b) { a = (f32x4){bf_lo(w.x), bf_hi(w.x), bf_lo(w.y), bf_hi(w.y)}; b = (f32x4){bf_lo(w.z), bf_hi(w.z), bf_lo(w.w), bf_hi(w.w)}; }
;     __device__ __forceinline__ void operator()(const f32x4 (&acc)[2][2][4][2], const Unit& u, int wr, int wc, int fr, int fq) const {
;     ...
;                     } else if (MODE == EP_RESID) {
;                         f32x4 x0, x1; unpack8(*(const u32x4*)(xb + row * ldc + col), x0, x1); x0 = x0 + v0; x1 = x1 + v1;
;                         if (O) { *(f32x4*)((float*)O + row * ldc + col) = x0; *(f32x4*)((float*)O + row * ldc + col + 4) = x1; }
.LBB0_431:
	s_nop 0
	s_and_b64 vcc, exec, s[4:5]
	s_nop 0
	s_waitcnt vmcnt(10)
	v_lshlrev_b32_e32 v94, 16, v212
	v_and_b32_e32 v95, 0xffff0000, v212
	v_lshlrev_b32_e32 v90, 16, v213
	v_and_b32_e32 v91, 0xffff0000, v213
	v_lshlrev_b32_e32 v96, 16, v214
	v_and_b32_e32 v97, 0xffff0000, v214
	v_lshlrev_b32_e32 v92, 16, v215
	v_and_b32_e32 v93, 0xffff0000, v215
	v_pk_add_f32 v[88:89], v[88:89], v[90:91]
	v_pk_add_f32 v[86:87], v[86:87], v[94:95]
	v_pk_add_f32 v[84:85], v[84:85], v[92:93]
	v_pk_add_f32 v[82:83], v[82:83], v[96:97]
	s_cbranch_vccnz .LBB0_433
	v_lshl_add_u64 v[90:91], v[142:143], 2, v[100:101]
	global_store_dwordx4 v[90:91], v[86:89], off offset:512
	global_store_dwordx4 v[90:91], v[82:85], off offset:528

; __device__ __forceinline__ void unpack8(u32x4 w, f32x4& a, f32x4& b) { a = (f32x4){bf_lo(w.x), bf_hi(w.x), bf_lo(w.y), bf_hi(w.y)}; b = (f32x4){bf_lo(w.z), bf_hi(w.z), bf_lo(w.w), bf_hi(w.w)}; }
;     __device__ __forceinline__ void operator()(const f32x4 (&acc)[2][2][4][2], const Unit& u, int wr, int wc, int fr, int fq) const {
;     ...
;                     } else if (MODE == EP_RESID) {
;                         f32x4 x0, x1; unpack8(*(const u32x4*)(xb + row * ldc + col), x0, x1); x0 = x0 + v0; x1 = x1 + v1;
;                         if (O) { *(f32x4*)((float*)O + row * ldc + col) = x0; *(f32x4*)((float*)O + row * ldc + col + 4) = x1; }
.LBB0_437:
	v_or_b32_e32 v88, 48, v140
	v_ashrrev_i32_e32 v89, 31, v88
	v_readlane_b32 s24, v253, 60
	v_lshlrev_b64 v[82:83], 12, v[88:89]
	v_readlane_b32 s25, v253, 61
	v_lshlrev_b64 v[88:89], 11, v[88:89]
	s_and_b64 vcc, exec, s[4:5]
	v_lshl_add_u64 v[82:83], s[24:25], 0, v[82:83]
	v_lshl_add_u64 v[82:83], v[142:143], 1, v[82:83]
	s_waitcnt lgkmcnt(0)
	s_nop 0
	s_nop 0
	s_waitcnt vmcnt(9)
	v_lshlrev_b32_e32 v90, 16, v216
	v_and_b32_e32 v91, 0xffff0000, v216
	v_lshlrev_b32_e32 v84, 16, v217
	v_and_b32_e32 v85, 0xffff0000, v217
	v_lshlrev_b32_e32 v92, 16, v218
	v_and_b32_e32 v93, 0xffff0000, v218
	v_lshlrev_b32_e32 v86, 16, v219
	v_and_b32_e32 v87, 0xffff0000, v219
	v_pk_add_f32 v[80:81], v[80:81], v[84:85]
	v_pk_add_f32 v[78:79], v[78:79], v[90:91]
	v_pk_add_f32 v[76:77], v[76:77], v[86:87]
	v_pk_add_f32 v[74:75], v[74:75], v[92:93]
	v_lshl_add_u64 v[84:85], v[88:89], 2, s[2:3]
	s_cbranch_vccnz .LBB0_439
	v_lshl_add_u64 v[86:87], v[142:143], 2, v[84:85]
	global_store_dwordx4 v[86:87], v[78:81], off
	global_store_dwordx4 v[86:87], v[74:77], off offset:16

; __device__ __forceinline__ void unpack8(u32x4 w, f32x4& a, f32x4& b) { a = (f32x4){bf_lo(w.x), bf_hi(w.x), bf_lo(w.y), bf_hi(w.y)}; b = (f32x4){bf_lo(w.z), bf_hi(w.z), bf_lo(w.w), bf_hi(w.w)}; }
;     __device__ __forceinline__ void operator()(const f32x4 (&acc)[2][2][4][2], const Unit& u, int wr, int wc, int fr, int fq) const {
;     ...
;                     } else if (MODE == EP_RESID) {
;                         f32x4 x0, x1; unpack8(*(const u32x4*)(xb + row * ldc + col), x0, x1); x0 = x0 + v0; x1 = x1 + v1;
;                         if (O) { *(f32x4*)((float*)O + row * ldc + col) = x0; *(f32x4*)((float*)O + row * ldc + col + 4) = x1; }
.LBB0_441:
	s_nop 0
	s_and_b64 vcc, exec, s[4:5]
	s_nop 0
	s_waitcnt vmcnt(8)
	v_lshlrev_b32_e32 v78, 16, v220
	v_and_b32_e32 v79, 0xffff0000, v220
	v_lshlrev_b32_e32 v74, 16, v221
	v_and_b32_e32 v75, 0xffff0000, v221
	v_lshlrev_b32_e32 v80, 16, v222
	v_and_b32_e32 v81, 0xffff0000, v222
	v_lshlrev_b32_e32 v76, 16, v223
	v_and_b32_e32 v77, 0xffff0000, v223
	v_pk_add_f32 v[72:73], v[72:73], v[74:75]
	v_pk_add_f32 v[70:71], v[70:71], v[78:79]
	v_pk_add_f32 v[68:69], v[68:69], v[76:77]
	v_pk_add_f32 v[66:67], v[66:67], v[80:81]
	s_cbranch_vccnz .LBB0_443
	v_lshl_add_u64 v[74:75], v[142:143], 2, v[84:85]
	global_store_dwordx4 v[74:75], v[70:73], off offset:512
	global_store_dwordx4 v[74:75], v[66:69], off offset:528

; __device__ __forceinline__ void unpack8(u32x4 w, f32x4& a, f32x4& b) { a = (f32x4){bf_lo(w.x), bf_hi(w.x), bf_lo(w.y), bf_hi(w.y)}; b = (f32x4){bf_lo(w.z), bf_hi(w.z), bf_lo(w.w), bf_hi(w.w)}; }
;     __device__ __forceinline__ void operator()(const f32x4 (&acc)[2][2][4][2], const Unit& u, int wr, int wc, int fr, int fq) const {
;     ...
;                     } else if (MODE == EP_RESID) {
;                         f32x4 x0, x1; unpack8(*(const u32x4*)(xb + row * ldc + col), x0, x1); x0 = x0 + v0; x1 = x1 + v1;
;                         if (O) { *(f32x4*)((float*)O + row * ldc + col) = x0; *(f32x4*)((float*)O + row * ldc + col + 4) = x1; }
.LBB0_447:
	v_add_u32_e32 v72, 0x80, v140
	v_ashrrev_i32_e32 v73, 31, v72
	v_readlane_b32 s24, v253, 60
	v_lshlrev_b64 v[66:67], 12, v[72:73]
	v_readlane_b32 s25, v253, 61
	v_lshlrev_b64 v[72:73], 11, v[72:73]
	s_and_b64 vcc, exec, s[4:5]
	v_lshl_add_u64 v[66:67], s[24:25], 0, v[66:67]
	v_lshl_add_u64 v[66:67], v[142:143], 1, v[66:67]
	s_waitcnt lgkmcnt(0)
	s_nop 0
	s_nop 0
	s_waitcnt vmcnt(7)
	v_lshlrev_b32_e32 v74, 16, v224
	v_and_b32_e32 v75, 0xffff0000, v224
	v_lshlrev_b32_e32 v68, 16, v225
	v_and_b32_e32 v69, 0xffff0000, v225
	v_lshlrev_b32_e32 v76, 16, v226
	v_and_b32_e32 v77, 0xffff0000, v226
	v_lshlrev_b32_e32 v70, 16, v227
	v_and_b32_e32 v71, 0xffff0000, v227
	v_pk_add_f32 v[64:65], v[64:65], v[68:69]
	v_pk_add_f32 v[62:63], v[62:63], v[74:75]
	v_pk_add_f32 v[60:61], v[60:61], v[70:71]
	v_pk_add_f32 v[58:59], v[58:59], v[76:77]
	v_lshl_add_u64 v[68:69], v[72:73], 2, s[2:3]
	s_cbranch_vccnz .LBB0_449
	v_lshl_add_u64 v[70:71], v[142:143], 2, v[68:69]
	global_store_dwordx4 v[70:71], v[62:65], off
	global_store_dwordx4 v[70:71], v[58:61], off offset:16

; __device__ __forceinline__ void unpack8(u32x4 w, f32x4& a, f32x4& b) { a = (f32x4){bf_lo(w.x), bf_hi(w.x), bf_lo(w.y), bf_hi(w.y)}; b = (f32x4){bf_lo(w.z), bf_hi(w.z), bf_lo(w.w), bf_hi(w.w)}; }
;     __device__ __forceinline__ void operator()(const f32x4 (&acc)[2][2][4][2], const Unit& u, int wr, int wc, int fr, int fq) const {
;     ...
;                     } else if (MODE == EP_RESID) {
;                         f32x4 x0, x1; unpack8(*(const u32x4*)(xb + row * ldc + col), x0, x1); x0 = x0 + v0; x1 = x1 + v1;
;                         if (O) { *(f32x4*)((float*)O + row * ldc + col) = x0; *(f32x4*)((float*)O + row * ldc + col + 4) = x1; }
.LBB0_451:
	s_nop 0
	s_and_b64 vcc, exec, s[4:5]
	s_nop 0
	s_waitcnt vmcnt(6)
	v_lshlrev_b32_e32 v62, 16, v228
	v_and_b32_e32 v63, 0xffff0000, v228
	v_lshlrev_b32_e32 v58, 16, v229
	v_and_b32_e32 v59, 0xffff0000, v229
	v_lshlrev_b32_e32 v64, 16, v230
	v_and_b32_e32 v65, 0xffff0000, v230
	v_lshlrev_b32_e32 v60, 16, v231
	v_and_b32_e32 v61, 0xffff0000, v231
	v_pk_add_f32 v[56:57], v[56:57], v[58:59]
	v_pk_add_f32 v[54:55], v[54:55], v[62:63]
	v_pk_add_f32 v[52:53], v[52:53], v[60:61]
	v_pk_add_f32 v[50:51], v[50:51], v[64:65]
	s_cbranch_vccnz .LBB0_453
	v_lshl_add_u64 v[58:59], v[142:143], 2, v[68:69]
	global_store_dwordx4 v[58:59], v[54:57], off offset:512
	global_store_dwordx4 v[58:59], v[50:53], off offset:528

; __device__ __forceinline__ void unpack8(u32x4 w, f32x4& a, f32x4& b) { a = (f32x4){bf_lo(w.x), bf_hi(w.x), bf_lo(w.y), bf_hi(w.y)}; b = (f32x4){bf_lo(w.z), bf_hi(w.z), bf_lo(w.w), bf_hi(w.w)}; }
;     __device__ __forceinline__ void operator()(const f32x4 (&acc)[2][2][4][2], const Unit& u, int wr, int wc, int fr, int fq) const {
;     ...
;                     } else if (MODE == EP_RESID) {
;                         f32x4 x0, x1; unpack8(*(const u32x4*)(xb + row * ldc + col), x0, x1); x0 = x0 + v0; x1 = x1 + v1;
;                         if (O) { *(f32x4*)((float*)O + row * ldc + col) = x0; *(f32x4*)((float*)O + row * ldc + col + 4) = x1; }
.LBB0_457:
	v_add_u32_e32 v56, 0x90, v140
	v_ashrrev_i32_e32 v57, 31, v56
	v_readlane_b32 s24, v253, 60
	v_lshlrev_b64 v[50:51], 12, v[56:57]
	v_readlane_b32 s25, v253, 61
	v_lshlrev_b64 v[56:57], 11, v[56:57]
	s_and_b64 vcc, exec, s[4:5]
	v_lshl_add_u64 v[50:51], s[24:25], 0, v[50:51]
	v_lshl_add_u64 v[50:51], v[142:143], 1, v[50:51]
	s_waitcnt lgkmcnt(0)
	s_nop 0
	s_nop 0
	s_waitcnt vmcnt(5)
	v_lshlrev_b32_e32 v58, 16, v232
	v_and_b32_e32 v59, 0xffff0000, v232
	v_lshlrev_b32_e32 v52, 16, v233
	v_and_b32_e32 v53, 0xffff0000, v233
	v_lshlrev_b32_e32 v60, 16, v234
	v_and_b32_e32 v61, 0xffff0000, v234
	v_lshlrev_b32_e32 v54, 16, v235
	v_and_b32_e32 v55, 0xffff0000, v235
	v_pk_add_f32 v[48:49], v[48:49], v[52:53]
	v_pk_add_f32 v[46:47], v[46:47], v[58:59]
	v_pk_add_f32 v[44:45], v[44:45], v[54:55]
	v_pk_add_f32 v[42:43], v[42:43], v[60:61]
	v_lshl_add_u64 v[52:53], v[56:57], 2, s[2:3]
	s_cbranch_vccnz .LBB0_459
	v_lshl_add_u64 v[54:55], v[142:143], 2, v[52:53]
	global_store_dwordx4 v[54:55], v[46:49], off
	global_store_dwordx4 v[54:55], v[42:45], off offset:16

; __device__ __forceinline__ void unpack8(u32x4 w, f32x4& a, f32x4& b) { a = (f32x4){bf_lo(w.x), bf_hi(w.x), bf_lo(w.y), bf_hi(w.y)}; b = (f32x4){bf_lo(w.z), bf_hi(w.z), bf_lo(w.w), bf_hi(w.w)}; }
;     __device__ __forceinline__ void operator()(const f32x4 (&acc)[2][2][4][2], const Unit& u, int wr, int wc, int fr, int fq) const {
;     ...
;                     } else if (MODE == EP_RESID) {
;                         f32x4 x0, x1; unpack8(*(const u32x4*)(xb + row * ldc + col), x0, x1); x0 = x0 + v0; x1 = x1 + v1;
;                         if (O) { *(f32x4*)((float*)O + row * ldc + col) = x0; *(f32x4*)((float*)O + row * ldc + col + 4) = x1; }
.LBB0_461:
	s_nop 0
	s_and_b64 vcc, exec, s[4:5]
	s_nop 0
	s_waitcnt vmcnt(4)
	v_lshlrev_b32_e32 v46, 16, v236
	v_and_b32_e32 v47, 0xffff0000, v236
	v_lshlrev_b32_e32 v42, 16, v237
	v_and_b32_e32 v43, 0xffff0000, v237
	v_lshlrev_b32_e32 v48, 16, v238
	v_and_b32_e32 v49, 0xffff0000, v238
	v_lshlrev_b32_e32 v44, 16, v239
	v_and_b32_e32 v45, 0xffff0000, v239
	v_pk_add_f32 v[40:41], v[40:41], v[42:43]
	v_pk_add_f32 v[38:39], v[38:39], v[46:47]
	v_pk_add_f32 v[36:37], v[36:37], v[44:45]
	v_pk_add_f32 v[34:35], v[34:35], v[48:49]
	s_cbranch_vccnz .LBB0_463
	v_lshl_add_u64 v[42:43], v[142:143], 2, v[52:53]
	global_store_dwordx4 v[42:43], v[38:41], off offset:512
	global_store_dwordx4 v[42:43], v[34:37], off offset:528

; __device__ __forceinline__ void unpack8(u32x4 w, f32x4& a, f32x4& b) { a = (f32x4){bf_lo(w.x), bf_hi(w.x), bf_lo(w.y), bf_hi(w.y)}; b = (f32x4){bf_lo(w.z), bf_hi(w.z), bf_lo(w.w), bf_hi(w.w)}; }
;     __device__ __forceinline__ void operator()(const f32x4 (&acc)[2][2][4][2], const Unit& u, int wr, int wc, int fr, int fq) const {
;     ...
;                     } else if (MODE == EP_RESID) {
;                         f32x4 x0, x1; unpack8(*(const u32x4*)(xb + row * ldc + col), x0, x1); x0 = x0 + v0; x1 = x1 + v1;
;                         if (O) { *(f32x4*)((float*)O + row * ldc + col) = x0; *(f32x4*)((float*)O + row * ldc + col + 4) = x1; }
.LBB0_467:
	v_add_u32_e32 v40, 0xa0, v140
	v_ashrrev_i32_e32 v41, 31, v40
	v_readlane_b32 s24, v253, 60
	v_lshlrev_b64 v[34:35], 12, v[40:41]
	v_readlane_b32 s25, v253, 61
	v_lshlrev_b64 v[40:41], 11, v[40:41]
	s_and_b64 vcc, exec, s[4:5]
	v_lshl_add_u64 v[34:35], s[24:25], 0, v[34:35]
	v_lshl_add_u64 v[34:35], v[142:143], 1, v[34:35]
	s_waitcnt lgkmcnt(0)
	s_nop 0
	s_nop 0
	s_waitcnt vmcnt(3)
	v_lshlrev_b32_e32 v42, 16, v206
	v_and_b32_e32 v43, 0xffff0000, v206
	v_lshlrev_b32_e32 v36, 16, v207
	v_and_b32_e32 v37, 0xffff0000, v207
	v_lshlrev_b32_e32 v44, 16, v208
	v_and_b32_e32 v45, 0xffff0000, v208
	v_lshlrev_b32_e32 v38, 16, v209
	v_and_b32_e32 v39, 0xffff0000, v209
	v_pk_add_f32 v[32:33], v[32:33], v[36:37]
	v_pk_add_f32 v[30:31], v[30:31], v[42:43]
	v_pk_add_f32 v[28:29], v[28:29], v[38:39]
	v_pk_add_f32 v[26:27], v[26:27], v[44:45]
	v_lshl_add_u64 v[36:37], v[40:41], 2, s[2:3]
	s_cbranch_vccnz .LBB0_469
	v_lshl_add_u64 v[38:39], v[142:143], 2, v[36:37]
	global_store_dwordx4 v[38:39], v[30:33], off
	global_store_dwordx4 v[38:39], v[26:29], off offset:16

; __device__ __forceinline__ void unpack8(u32x4 w, f32x4& a, f32x4& b) { a = (f32x4){bf_lo(w.x), bf_hi(w.x), bf_lo(w.y), bf_hi(w.y)}; b = (f32x4){bf_lo(w.z), bf_hi(w.z), bf_lo(w.w), bf_hi(w.w)}; }
;     __device__ __forceinline__ void operator()(const f32x4 (&acc)[2][2][4][2], const Unit& u, int wr, int wc, int fr, int fq) const {
;     ...
;                     } else if (MODE == EP_RESID) {
;                         f32x4 x0, x1; unpack8(*(const u32x4*)(xb + row * ldc + col), x0, x1); x0 = x0 + v0; x1 = x1 + v1;
;                         if (O) { *(f32x4*)((float*)O + row * ldc + col) = x0; *(f32x4*)((float*)O + row * ldc + col + 4) = x1; }
.LBB0_471:
	s_nop 0
	s_and_b64 vcc, exec, s[4:5]
	s_nop 0
	s_waitcnt vmcnt(2)
	v_lshlrev_b32_e32 v30, 16, v172
	v_and_b32_e32 v31, 0xffff0000, v172
	v_lshlrev_b32_e32 v26, 16, v173
	v_and_b32_e32 v27, 0xffff0000, v173
	v_lshlrev_b32_e32 v32, 16, v174
	v_and_b32_e32 v33, 0xffff0000, v174
	v_lshlrev_b32_e32 v28, 16, v175
	v_and_b32_e32 v29, 0xffff0000, v175
	v_pk_add_f32 v[24:25], v[24:25], v[26:27]
	v_pk_add_f32 v[22:23], v[22:23], v[30:31]
	v_pk_add_f32 v[20:21], v[20:21], v[28:29]
	v_pk_add_f32 v[18:19], v[18:19], v[32:33]
	s_cbranch_vccnz .LBB0_473
	v_lshl_add_u64 v[26:27], v[142:143], 2, v[36:37]
	global_store_dwordx4 v[26:27], v[22:25], off offset:512
	global_store_dwordx4 v[26:27], v[18:21], off offset:528

; __device__ __forceinline__ void unpack8(u32x4 w, f32x4& a, f32x4& b) { a = (f32x4){bf_lo(w.x), bf_hi(w.x), bf_lo(w.y), bf_hi(w.y)}; b = (f32x4){bf_lo(w.z), bf_hi(w.z), bf_lo(w.w), bf_hi(w.w)}; }
;     __device__ __forceinline__ void operator()(const f32x4 (&acc)[2][2][4][2], const Unit& u, int wr, int wc, int fr, int fq) const {
;     ...
;                     } else if (MODE == EP_RESID) {
;                         f32x4 x0, x1; unpack8(*(const u32x4*)(xb + row * ldc + col), x0, x1); x0 = x0 + v0; x1 = x1 + v1;
;                         if (O) { *(f32x4*)((float*)O + row * ldc + col) = x0; *(f32x4*)((float*)O + row * ldc + col + 4) = x1; }
.LBB0_477:
	v_add_u32_e32 v24, 0xb0, v140
	v_ashrrev_i32_e32 v25, 31, v24
	v_readlane_b32 s24, v253, 60
	v_lshlrev_b64 v[18:19], 12, v[24:25]
	v_readlane_b32 s25, v253, 61
	v_lshlrev_b64 v[24:25], 11, v[24:25]
	s_and_b64 vcc, exec, s[4:5]
	v_lshl_add_u64 v[18:19], s[24:25], 0, v[18:19]
	v_lshl_add_u64 v[18:19], v[142:143], 1, v[18:19]
	s_waitcnt lgkmcnt(0)
	s_nop 0
	s_nop 0
	s_waitcnt vmcnt(1)
	v_lshlrev_b32_e32 v26, 16, v176
	v_and_b32_e32 v27, 0xffff0000, v176
	v_lshlrev_b32_e32 v20, 16, v177
	v_and_b32_e32 v21, 0xffff0000, v177
	v_lshlrev_b32_e32 v28, 16, v178
	v_and_b32_e32 v29, 0xffff0000, v178
	v_lshlrev_b32_e32 v22, 16, v179
	v_and_b32_e32 v23, 0xffff0000, v179
	v_pk_add_f32 v[16:17], v[16:17], v[20:21]
	v_pk_add_f32 v[14:15], v[14:15], v[26:27]
	v_pk_add_f32 v[12:13], v[12:13], v[22:23]
	v_pk_add_f32 v[10:11], v[10:11], v[28:29]
	v_lshl_add_u64 v[20:21], v[24:25], 2, s[2:3]
	s_cbranch_vccnz .LBB0_479
	v_lshl_add_u64 v[22:23], v[142:143], 2, v[20:21]
	global_store_dwordx4 v[22:23], v[14:17], off
	global_store_dwordx4 v[22:23], v[10:13], off offset:16

; __device__ __forceinline__ void unpack8(u32x4 w, f32x4& a, f32x4& b) { a = (f32x4){bf_lo(w.x), bf_hi(w.x), bf_lo(w.y), bf_hi(w.y)}; b = (f32x4){bf_lo(w.z), bf_hi(w.z), bf_lo(w.w), bf_hi(w.w)}; }
;     __device__ __forceinline__ void operator()(const f32x4 (&acc)[2][2][4][2], const Unit& u, int wr, int wc, int fr, int fq) const {
;     ...
;                     } else if (MODE == EP_RESID) {
;                         f32x4 x0, x1; unpack8(*(const u32x4*)(xb + row * ldc + col), x0, x1); x0 = x0 + v0; x1 = x1 + v1;
;                         if (O) { *(f32x4*)((float*)O + row * ldc + col) = x0; *(f32x4*)((float*)O + row * ldc + col + 4) = x1; }
.LBB0_481:
	s_nop 0
	s_and_b64 vcc, exec, s[4:5]
	s_nop 0
	s_waitcnt vmcnt(0)
	v_lshlrev_b32_e32 v14, 16, v180
	v_and_b32_e32 v15, 0xffff0000, v180
	v_lshlrev_b32_e32 v10, 16, v181
	v_and_b32_e32 v11, 0xffff0000, v181
	v_lshlrev_b32_e32 v16, 16, v182
	v_and_b32_e32 v17, 0xffff0000, v182
	v_lshlrev_b32_e32 v12, 16, v183
	v_and_b32_e32 v13, 0xffff0000, v183
	v_pk_add_f32 v[8:9], v[8:9], v[10:11]
	v_pk_add_f32 v[6:7], v[6:7], v[14:15]
	v_pk_add_f32 v[4:5], v[4:5], v[12:13]
	v_pk_add_f32 v[2:3], v[2:3], v[16:17]
	s_cbranch_vccnz .LBB0_483
	v_lshl_add_u64 v[10:11], v[142:143], 2, v[20:21]
	global_store_dwordx4 v[10:11], v[6:9], off offset:512
	global_store_dwordx4 v[10:11], v[2:5], off offset:528

; __global__ void __launch_bounds__(NTHR, 2) fwd(Args a) {
	.amdhsa_kernel _ZN2mk3fwdENS_4ArgsE
		.amdhsa_group_segment_fixed_size 0
		.amdhsa_private_segment_fixed_size 0
		.amdhsa_kernarg_size 520
		.amdhsa_user_sgpr_count 2
		.amdhsa_user_sgpr_dispatch_ptr 0
		.amdhsa_user_sgpr_queue_ptr 0
		.amdhsa_user_sgpr_kernarg_segment_ptr 1
		.amdhsa_user_sgpr_dispatch_id 0
		.amdhsa_user_sgpr_kernarg_preload_length 0
		.amdhsa_user_sgpr_kernarg_preload_offset 0
		.amdhsa_user_sgpr_private_segment_size 0
		.amdhsa_uses_dynamic_stack 0
		.amdhsa_enable_private_segment 0
		.amdhsa_system_sgpr_workgroup_id_x 1
		.amdhsa_system_sgpr_workgroup_id_y 0
		.amdhsa_system_sgpr_workgroup_id_z 0
		.amdhsa_system_sgpr_workgroup_info 0
		.amdhsa_system_vgpr_workitem_id 2
		.amdhsa_next_free_vgpr 256
		.amdhsa_next_free_sgpr 100
		.amdhsa_accum_offset 256
		.amdhsa_reserve_vcc 1
		.amdhsa_float_round_mode_32 0
		.amdhsa_float_round_mode_16_64 0
		.amdhsa_float_denorm_mode_32 3
		.amdhsa_float_denorm_mode_16_64 3
		.amdhsa_dx10_clamp 1
		.amdhsa_ieee_mode 1
		.amdhsa_fp16_overflow 0
		.amdhsa_tg_split 0
		.amdhsa_exception_fp_ieee_invalid_op 0
		.amdhsa_exception_fp_denorm_src 0
		.amdhsa_exception_fp_ieee_div_zero 0
		.amdhsa_exception_fp_ieee_overflow 0
		.amdhsa_exception_fp_ieee_underflow 0
		.amdhsa_exception_fp_ieee_inexact 0
		.amdhsa_exception_int_div_zero 0
	.end_amdhsa_kernel

; __global__ void __launch_bounds__(NTHR, 2) fwd(Args a) {
amdhsa.kernels:
  - .agpr_count:     0
    .args:
      - .offset:         0
        .size:           264
        .value_kind:     by_value
      - .offset:         264
        .size:           4
        .value_kind:     hidden_block_count_x
      - .offset:         268
        .size:           4
        .value_kind:     hidden_block_count_y
      - .offset:         272
        .size:           4
        .value_kind:     hidden_block_count_z
      - .offset:         276
        .size:           2
        .value_kind:     hidden_group_size_x
      - .offset:         278
        .size:           2
        .value_kind:     hidden_group_size_y
      - .offset:         280
        .size:           2
        .value_kind:     hidden_group_size_z
      - .offset:         282
        .size:           2
        .value_kind:     hidden_remainder_x
      - .offset:         284
        .size:           2
        .value_kind:     hidden_remainder_y
      - .offset:         286
        .size:           2
        .value_kind:     hidden_remainder_z
      - .offset:         304
        .size:           8
        .value_kind:     hidden_global_offset_x
      - .offset:         312
        .size:           8
        .value_kind:     hidden_global_offset_y
      - .offset:         320
        .size:           8
        .value_kind:     hidden_global_offset_z
      - .offset:         328
        .size:           2
        .value_kind:     hidden_grid_dims
      - .offset:         352
        .size:           8
        .value_kind:     hidden_multigrid_sync_arg
      - .offset:         384
        .size:           4
        .value_kind:     hidden_dynamic_lds_size
    .group_segment_fixed_size: 0
    .kernarg_segment_align: 8
    .kernarg_segment_size: 520
    .language:       OpenCL C
    .language_version:
      - 2
      - 0
    .max_flat_workgroup_size: 512
    .name:           _ZN2mk3fwdENS_4ArgsE
    .private_segment_fixed_size: 0
    .sgpr_count:     106
    .sgpr_spill_count: 291
    .symbol:         _ZN2mk3fwdENS_4ArgsE.kd
    .uniform_work_group_size: 1
    .uses_dynamic_stack: false
    .vgpr_count:     256
    .vgpr_spill_count: 0
    .wavefront_size: 64
